# P0 weight items: per-workgroup dynamic ticket queue in LDS instead of the static per-wave item list (same items, fast waves take more), on top of full-line epilogues + permlane ssq
# baseline (speedup 1.0000x reference)
.LBB0_7:
	s_bfe_i32 s4, s33, 0x1001c
	s_lshl_b32 s51, s33, 3
	s_lshr_b32 s3, s4, 26
	s_add_i32 s61, s51, s3
	s_ashr_i32 s3, s61, 6
	s_abs_i32 s3, s3
	v_cvt_f32_u32_e32 v2, s3
	s_bfe_i32 s5, s33, 0x1d0000
	s_abs_i32 s59, s5
	v_cvt_f32_u32_e32 v3, s59
	v_rcp_iflag_f32_e32 v2, v2
	s_sub_i32 s5, 0, s3
	s_load_dwordx16 s[12:27], s[0:1], 0x48
	v_rcp_iflag_f32_e32 v3, v3
	v_mul_f32_e32 v2, 0x4f7ffffe, v2
	v_cvt_u32_f32_e32 v2, v2
	s_load_dwordx8 s[36:43], s[0:1], 0x0
	s_lshl_b32 s6, s2, 3
	v_and_b32_e32 v1, 63, v168
	v_readfirstlane_b32 s7, v2
	v_mul_f32_e32 v2, 0x4f7ffffe, v3
	v_cvt_u32_f32_e32 v2, v2
	s_mul_i32 s5, s5, s7
	s_mul_hi_u32 s5, s7, s5
	s_add_i32 s48, s7, s5
	s_sub_i32 s5, 0, s59
	v_readfirstlane_b32 s7, v2
	s_mul_i32 s5, s5, s7
	s_mul_hi_u32 s5, s7, s5
	s_add_i32 s50, s7, s5
	v_readfirstlane_b32 s5, v168
	s_lshr_b32 s5, s5, 6
	s_add_i32 s64, s5, s6
	s_lshl_b32 s95, s2, 3
	v_mov_b32_e32 v140, 0x23ffc
	v_mov_b32_e32 v141, 8
	v_cmp_eq_u32_e32 vcc, 0, v168
	s_and_saveexec_b64 s[92:93], vcc
	ds_write_b32 v140, v141
	s_or_b64 exec, exec, s[92:93]
	s_waitcnt lgkmcnt(0)
	s_barrier
	v_lshlrev_b32_e32 v85, 1, v168
	s_cmpk_gt_i32 s64, 0x39ff
	v_mov_b32_e32 v67, 0
	s_cbranch_scc1 .LBB0_100
	v_lshrrev_b32_e32 v68, 4, v1
	v_bfe_u32 v2, v168, 2, 2
	v_lshlrev_b32_e32 v66, 3, v68
	v_or_b32_e32 v4, v66, v2
	v_and_b32_e32 v2, 48, v1
	v_mov_b32_e32 v3, v67
	s_waitcnt lgkmcnt(0)
	v_lshl_add_u64 v[2:3], s[26:27], 0, v[2:3]
	s_mov_b64 s[6:7], 0x6200000
	v_lshl_add_u64 v[70:71], v[2:3], 0, s[6:7]
	s_mov_b64 s[6:7], 0x4200000
	v_lshl_add_u64 v[72:73], v[2:3], 0, s[6:7]
	v_lshl_add_u64 v[2:3], s[26:27], 0, v[66:67]
	s_mov_b64 s[6:7], 0x3a00000
	v_lshl_add_u64 v[74:75], v[2:3], 0, s[6:7]
	s_mov_b64 s[6:7], 0x3600200
	v_lshl_add_u64 v[76:77], v[2:3], 0, s[6:7]
	s_mov_b64 s[6:7], 0x3600000
	s_mov_b64 s[8:9], 0xe00000
	v_lshl_add_u64 v[78:79], v[2:3], 0, s[6:7]
	v_lshl_add_u64 v[80:81], v[2:3], 0, s[8:9]
	v_lshlrev_b32_e32 v3, 5, v168
	v_lshlrev_b32_e32 v2, 3, v1
	v_and_b32_e32 v3, 64, v3
	v_and_b32_e32 v89, 24, v2
	v_and_or_b32 v90, v2, 8, v3
	v_bfe_u32 v2, v168, 3, 1
	s_movk_i32 s10, 0x88
	v_or_b32_e32 v6, 60, v68
	v_and_or_b32 v91, v85, 14, v2
	v_mov_b32_e32 v2, 0xfffffde0
	v_mad_u32_u24 v99, v6, s10, v2
	v_mov_b32_e32 v2, 0xfffffbc0
	v_mad_u32_u24 v100, v6, s10, v2
	v_mov_b32_e32 v2, 0xfffff9a0
	v_mad_u32_u24 v101, v6, s10, v2
	v_mov_b32_e32 v2, 0xfffff780
	v_mad_u32_u24 v102, v6, s10, v2
	v_mov_b32_e32 v2, 0xfffff560
	v_mad_u32_u24 v103, v6, s10, v2
	v_mov_b32_e32 v2, 0xfffff340
	v_mad_u32_u24 v104, v6, s10, v2
	v_mov_b32_e32 v2, 0xfffff120
	v_mad_u32_u24 v105, v6, s10, v2
	v_mov_b32_e32 v2, 0xffffef00
	v_mad_u32_u24 v106, v6, s10, v2
	v_mov_b32_e32 v2, 0xffffece0
	v_mad_u32_u24 v107, v6, s10, v2
	v_mov_b32_e32 v2, 0xffffeac0
	v_mad_u32_u24 v108, v6, s10, v2
	v_mov_b32_e32 v2, 0xffffe8a0
	v_mad_u32_u24 v109, v6, s10, v2
	v_mov_b32_e32 v2, 0xffffe680
	v_mad_u32_u24 v110, v6, s10, v2
	v_mov_b32_e32 v2, 0xffffe460
	v_and_b32_e32 v86, 15, v168
	s_cmp_lg_u64 s[18:19], 0
	s_mul_i32 s8, s5, 0x2200
	v_mad_u32_u24 v111, v6, s10, v2
	v_mov_b32_e32 v2, 0xffffe240
	s_cselect_b64 s[52:53], -1, 0
	s_cmp_lg_u64 s[38:39], 0
	v_mad_u32_u24 v112, v6, s10, v2
	v_lshlrev_b32_e32 v2, 3, v168
	v_mul_u32_u24_e32 v3, 0x88, v68
	v_lshl_or_b32 v113, v86, 3, s8
	v_lshlrev_b32_e32 v87, 2, v86
	v_mul_u32_u24_e32 v5, 0x88, v4
	s_cselect_b64 s[54:55], -1, 0
	v_mul_u32_u24_e32 v98, 0x88, v6
	v_mov_b32_e32 v6, s8
	v_and_or_b32 v2, v2, 24, s8
	s_lshl_b32 s8, s64, 1
	v_add_u32_e32 v115, v113, v3
	v_cmp_gt_u32_e64 s[6:7], 8, v86
	v_add_u32_e32 v88, 32, v87
	v_or_b32_e32 v92, 16, v90
	v_or_b32_e32 v93, 32, v89
	v_or_b32_e32 v94, 32, v90
	v_or_b32_e32 v95, 64, v89
	v_or_b32_e32 v96, 48, v90
	v_or_b32_e32 v97, 0x60, v89
	v_mov_b32_e32 v69, v67
	v_mad_u32_u24 v114, v4, s10, v6
	s_lshl_b32 s65, s64, 6
	s_lshl_b32 s66, s51, 6
	s_lshl_b32 s67, s64, 5
	s_lshl_b32 s68, s51, 5
	s_add_i32 s69, s8, 0x1ac00
	s_lshl_b32 s70, s51, 1
	s_mov_b32 s57, 0
	s_mov_b32 s71, 0x8000
	s_mov_b32 s72, 0x10000
	s_mov_b32 s73, 0x20000
	s_mov_b32 s74, 0x40000
	v_add_u32_e32 v116, v2, v5
	s_mov_b32 s75, 0x80000
	s_mov_b32 s58, 0x42800000
	s_mov_b32 s60, 0x42000000
	s_movk_i32 s76, 0x4000
	s_mov_b32 s77, 0xa000
	v_add_u32_e32 v117, 0x800, v115
	v_add_u32_e32 v118, 0x1000, v115
	v_add_u32_e32 v119, 0x1800, v115
	v_mov_b32_e32 v120, 0xc0000
	v_cndmask_b32_e64 v121, 0, 1, s[52:53]
	v_mov_b32_e32 v122, 0x30000
	v_mov_b32_e32 v123, 0x18000
	v_mov_b32_e32 v124, 0xc000
	s_branch .LBB0_12

.LBB0_11:
	s_mov_b64 s[92:93], exec
	s_mov_b64 exec, 1
	v_mov_b32_e32 v140, 0x23ffc
	v_mov_b32_e32 v141, 1
	ds_add_rtn_u32 v142, v140, v141
	s_waitcnt lgkmcnt(0)
	v_readfirstlane_b32 s94, v142
	s_mov_b64 exec, s[92:93]
	s_nop 1
	s_and_b32 s64, s94, 7
	s_lshr_b32 s94, s94, 3
	s_lshl_b32 s94, s94, 11
	s_add_i32 s64, s64, s94
	s_add_i32 s64, s64, s95
	s_lshl_b32 s65, s64, 6
	s_lshl_b32 s67, s64, 5
	s_lshl_b32 s69, s64, 1
	s_add_i32 s69, s69, 0x1ac00
	s_cmpk_gt_i32 s64, 0x39ff
	s_cbranch_scc1 .LBB0_100
